# p0stride: phase-0 weight tiles assigned round-robin (tile t -> block t%256, 41 each) instead of contiguous ranges; rest = v95
# baseline (speedup 1.0000x reference)
; #define LAS __attribute__((address_space(3)))
; __device__ __forceinline__ unsigned xb_add(unsigned* p, unsigned v) { return __hip_atomic_fetch_add(p, v, __ATOMIC_RELAXED, __HIP_MEMORY_SCOPE_AGENT); }
; __device__ __forceinline__ unsigned xb_xcc_id() { return (unsigned)__builtin_amdgcn_s_getreg((3 << 11) | 20) & 0xFu; }
; __device__ __forceinline__ XcdBarrier xcd_barrier_post(unsigned* bar, volatile LAS unsigned* st) {
;     XcdBarrier b; b.bar = bar; b.x = xb_xcc_id(); b.st = st;
;     if (threadIdx.x == 0) (void)xb_add(&bar[XB_XCNT(b.x)], 1u);
;     return b;
; }
; __global__ void __launch_bounds__(512, 2) mega(Params P, int ph0, int ph1) {
;     extern __shared__ __attribute__((aligned(16))) unsigned char shm[];
;     __shared__ uint4 xb_words;
;     if (threadIdx.x == 0) xb_words = make_uint4(0u, 0u, 0u, 0u);
;     __syncthreads();
;     const XcdBarrier xb = xcd_barrier_post((unsigned*)(P.ws + O_BAR), (volatile LAS unsigned*)&xb_words);
_Z4mega6Paramsii:
	s_nop 0
	s_load_dwordx2 s[88:89], s[0:1], 0xd0
	s_mov_b32 s84, s2
	s_mov_b64 s[86:87], s[0:1]
	v_cmp_eq_u32_e64 s[92:93], 0, v0
	s_and_saveexec_b64 s[4:5], s[92:93]
	v_mov_b32_e32 v2, 0
	v_mov_b32_e32 v3, v2
	v_mov_b32_e32 v4, v2
	v_mov_b32_e32 v5, v2
	ds_write_b128 v2, v[2:5]
	s_or_b64 exec, exec, s[4:5]
	s_waitcnt lgkmcnt(0)
	s_barrier
	s_add_u32 s90, s88, 0x2e9d8000
	s_getreg_b32 s0, hwreg(HW_REG_XCC_ID, 0, 4)
	s_addc_u32 s91, s89, 0
	s_and_b32 s85, s0, 15
	s_and_saveexec_b64 s[4:5], s[92:93]
	s_cbranch_execz .LBB0_5
	s_mov_b64 s[6:7], exec
	v_mbcnt_lo_u32_b32 v1, s6, 0
	v_mbcnt_hi_u32_b32 v1, s7, v1
	v_cmp_eq_u32_e32 vcc, 0, v1
	s_and_b64 s[0:1], exec, vcc
	s_mov_b64 exec, s[0:1]
	s_cbranch_execz .LBB0_5
	s_lshl_b32 s0, s85, 8
	s_bcnt1_i32_b64 s1, s[6:7]
	v_mov_b32_e32 v1, s0
	v_mov_b32_e32 v2, s1
	global_atomic_add v1, v2, s[90:91] offset:1024

; __device__ __forceinline__ int tid_opaque() { int t = threadIdx.x; asm volatile("" : "+v"(t)); return t; }
; __device__ __forceinline__ void phase_prep(PREF P, unsigned char* shm) {
;     ...
;     const int total = 2 * TILES_PER_LAYER; int start, cnt;
;     if (G == 256) { if (b < 64) { start = b * 38; cnt = 38; } else if (b < 81) { start = 2432 + (b - 64) * 42; cnt = 42; } else { start = 2432 + 17 * 42 + (b - 81) * 43; cnt = 43; } }
;     else { cnt = (total + G - 1) / G; start = b * cnt; }
;     const int end = (start + cnt) < total ? (start + cnt) : total;
;     const int tid = tid_opaque(), lr = tid >> 4, lc = (tid & 15) * 4;
;     if (start < end) {
;         int cur = start; TileJob J = tile_job(P, cur); f32x4 v[4];
.LBB0_219:
	s_add_i32 s0, s11, s0
	s_mov_b32 s11, s50
	s_movk_i32 s0, 0x2900
	s_min_i32 s0, s0, 0x2900
	v_mov_b32_e32 v20, v0
	s_cmp_ge_i32 s11, s0
	s_cbranch_scc1 .LBB0_258
	s_mul_hi_i32 s1, s11, 0x63e7063f
	s_load_dwordx2 s[4:5], s[6:7], 0xd0
	s_lshr_b32 s2, s1, 31
	s_ashr_i32 s1, s1, 11
	s_add_i32 s14, s1, s2
	s_mul_i32 s3, s14, 0xffffeb80
	s_add_i32 s3, s3, s11
	s_ashr_i32 s15, s14, 31
	s_mul_i32 s2, s14, 0x6e22000
	s_mul_hi_i32 s1, s14, 0x6e22000
	s_waitcnt lgkmcnt(0)
	s_add_u32 s12, s4, s2
	s_addc_u32 s13, s5, s1
	s_cmpk_gt_i32 s3, 0xdff
	s_cbranch_scc0 .LBB0_225
	s_cmpk_gt_u32 s3, 0x10ff
	s_cbranch_scc0 .LBB0_226
	s_cmpk_gt_u32 s3, 0x11ff
	s_cbranch_scc0 .LBB0_227
	s_cmpk_gt_u32 s3, 0x127f
	s_cbranch_scc0 .LBB0_228
	s_load_dwordx2 s[8:9], s[6:7], 0xc0
	s_lshl_b64 s[16:17], s[14:15], 24
	s_mov_b64 s[18:19], 0
	s_waitcnt lgkmcnt(0)
	s_add_u32 s16, s8, s16
	s_addc_u32 s17, s9, s17
	s_add_u32 s8, s12, 0x4e00000
	s_addc_u32 s9, s13, 0
	s_lshl_b32 s1, s3, 2
	s_andn2_b32 s1, s1, 63
	s_and_b32 s10, s11, 15
	s_addk_i32 s1, 0xb600
	s_branch .LBB0_229

; __device__ __forceinline__ int tid_opaque() { int t = threadIdx.x; asm volatile("" : "+v"(t)); return t; }
; __device__ __forceinline__ void phase_prep(PREF P, unsigned char* shm) {
;     ...
;     const int tid = tid_opaque(), lr = tid >> 4, lc = (tid & 15) * 4;
;     if (start < end) {
;         int cur = start; TileJob J = tile_job(P, cur); f32x4 v[4];
; #pragma unroll
;         for (int i = 0; i < 4; ++i) v[i] = *(const f32x4*)(J.src + (size_t)(J.k0 + lr + 32 * i) * J.N + J.n0 + lc);
;         for (;;) {
; #pragma unroll
;             for (int i = 0; i < 4; ++i)
; #pragma unroll
;                 for (int j = 0; j < 4; ++j) sm[(lr + 32 * i) * 65 + lc + j] = v[i][j];
;             __syncthreads();
;             const TileJob C = J; const bool more = cur + 1 < end;
;             if (more) { J = tile_job(P, cur + 1);
; #pragma unroll
;                 for (int i = 0; i < 4; ++i) v[i] = *(const f32x4*)(J.src + (size_t)(J.k0 + lr + 32 * i) * J.N + J.n0 + lc); }
;             const int n = tid >> 3, kg = tid & 7;
.LBB0_238:
	s_ashr_i32 s21, s20, 31
	v_ashrrev_i32_e32 v1, 4, v20
	v_lshlrev_b32_e32 v2, 2, v20
	s_lshl_b32 s12, s10, 7
	s_lshl_b64 s[14:15], s[20:21], 2
	v_and_b32_e32 v24, 60, v2
	v_add_u32_e32 v16, s12, v1
	s_add_u32 s14, s16, s14
	s_addc_u32 s15, s17, s15
	v_mov_b32_e32 v19, 0
	v_lshlrev_b32_e32 v18, 2, v24
	v_ashrrev_i32_e32 v2, 31, v16
	v_lshl_add_u64 v[10:11], s[14:15], 0, v[18:19]
	v_mul_lo_u32 v4, s18, v2
	v_mul_lo_u32 v5, s19, v16
	v_mad_u64_u32 v[2:3], s[14:15], s18, v16, 0
	v_add3_u32 v3, v3, v4, v5
	v_lshl_add_u64 v[12:13], v[2:3], 2, v[10:11]
	v_add_u32_e32 v2, 32, v16
	v_ashrrev_i32_e32 v3, 31, v2
	v_mul_lo_u32 v4, s18, v3
	v_mul_lo_u32 v5, s19, v2
	v_mad_u64_u32 v[2:3], s[14:15], s18, v2, 0
	v_add3_u32 v3, v3, v4, v5
	v_lshl_add_u64 v[14:15], v[2:3], 2, v[10:11]
	global_load_dwordx4 v[2:5], v[12:13], off
	global_load_dwordx4 v[6:9], v[14:15], off
	v_add_u32_e32 v12, 64, v16
	v_ashrrev_i32_e32 v13, 31, v12
	v_mul_lo_u32 v14, s18, v13
	v_mul_lo_u32 v15, s19, v12
	v_mad_u64_u32 v[12:13], s[14:15], s18, v12, 0
	v_add3_u32 v13, v13, v14, v15
	v_lshl_add_u64 v[22:23], v[12:13], 2, v[10:11]
	v_add_u32_e32 v12, 0x60, v16
	v_ashrrev_i32_e32 v13, 31, v12
	v_mul_lo_u32 v14, s18, v13
	v_mul_lo_u32 v15, s19, v12
	v_mad_u64_u32 v[12:13], s[14:15], s18, v12, 0
	v_add3_u32 v13, v13, v14, v15
	v_lshl_add_u64 v[26:27], v[12:13], 2, v[10:11]
	global_load_dwordx4 v[10:13], v[22:23], off
	global_load_dwordx4 v[14:17], v[26:27], off
	s_load_dwordx2 s[14:15], s[6:7], 0xc0
	s_load_dwordx2 s[16:17], s[6:7], 0xa0
	s_load_dwordx2 s[18:19], s[6:7], 0x40
	v_ashrrev_i32_e32 v22, 3, v20
	v_lshlrev_b32_e32 v20, 4, v20
	s_movk_i32 s3, 0x104
	v_add_u32_e32 v18, 16, v18
	v_and_b32_e32 v20, 0x70, v20
	v_mul_lo_u32 v23, v1, s3
	v_lshl_add_u32 v21, v22, 2, 16
	v_mul_u32_u24_e32 v25, 0x104, v20
	s_add_i32 s3, s11, 0x100
	s_lshl_b32 s10, s11, 2
	s_lshl_b32 s11, s11, 3
	v_add_u32_e32 v23, v18, v23
	s_add_i32 s10, s10, 0x400
	s_add_i32 s11, s11, 0x800
	s_movk_i32 s30, 0x90
	s_mov_b32 s13, 0
	s_movk_i32 s31, 0xb0
	v_lshlrev_b32_e32 v18, 2, v24
	v_lshlrev_b32_e32 v20, 1, v20
	v_add_u32_e32 v24, v21, v25
	v_add_u32_e32 v25, 0x2080, v23
	v_add_u32_e32 v26, 0x2088, v23
	s_mov_b32 s33, s1
	s_mov_b32 s40, s2
	s_mov_b64 s[22:23], s[8:9]
	s_branch .LBB0_241

; __device__ __forceinline__ u32x4 pack8(const float (&f)[8]) { u32x4 r; r[0] = cvt_pk_bf16(f[0], f[1]); r[1] = cvt_pk_bf16(f[2], f[3]); r[2] = cvt_pk_bf16(f[4], f[5]); r[3] = cvt_pk_bf16(f[6], f[7]); return r; }
; __device__ __forceinline__ void phase_prep(PREF P, unsigned char* shm) {
;     ...
;             const int n = tid >> 3, kg = tid & 7;
; #pragma unroll
;             for (int h = 0; h < 2; ++h) { float f[8];
; #pragma unroll
;                 for (int j = 0; j < 8; ++j) f[j] = sm[(kg * 16 + h * 8 + j) * 65 + n];
;                 *(u32x4*)(C.dst + (size_t)(C.drow0 + n) * C.K + C.k0 + kg * 16 + h * 8) = pack8(f); }
;             __syncthreads();
;             if (!more) break;
;             ++cur;
.LBB0_240:
	v_add_u32_e32 v21, s1, v22
	v_mad_u64_u32 v[28:29], s[26:27], v21, s2, 0
	v_ashrrev_i32_e32 v27, 31, v21
	v_mov_b32_e32 v30, v29
	v_mad_u64_u32 v[30:31], s[26:27], v27, s2, v[30:31]
	v_add_u32_e32 v27, 0x400, v24
	v_mov_b32_e32 v29, v30
	ds_read2_b32 v[30:31], v24 offset1:65
	ds_read2_b32 v[32:33], v24 offset0:130 offset1:195
	ds_read2_b32 v[34:35], v27 offset0:4 offset1:69
	ds_read2_b32 v[36:37], v27 offset0:134 offset1:199
	v_lshl_add_u64 v[28:29], v[28:29], 1, s[8:9]
	v_lshl_add_u64 v[28:29], s[12:13], 1, v[28:29]
	v_mov_b32_e32 v21, v19
	v_lshl_add_u64 v[38:39], v[28:29], 0, v[20:21]
	v_add_u32_e32 v21, 0x800, v24
	s_waitcnt lgkmcnt(3)
	v_cvt_pk_bf16_f32 v28, v30, v31
	s_waitcnt lgkmcnt(2)
	v_cvt_pk_bf16_f32 v29, v32, v33
	s_waitcnt lgkmcnt(1)
	v_cvt_pk_bf16_f32 v30, v34, v35
	s_waitcnt lgkmcnt(0)
	v_cvt_pk_bf16_f32 v31, v36, v37
	ds_read2_b32 v[32:33], v21 offset0:8 offset1:73
	ds_read2_b32 v[34:35], v21 offset0:138 offset1:203
	v_add_u32_e32 v21, 0xc00, v24
	ds_read2_b32 v[36:37], v21 offset0:12 offset1:77
	ds_read2_b32 v[40:41], v21 offset0:142 offset1:207
	s_add_i32 s3, s3, 0x100
	s_add_i32 s10, s10, 0x400
	s_add_i32 s11, s11, 0x800
	s_andn2_b64 vcc, exec, s[20:21]
	s_mov_b64 s[8:9], s[22:23]
	s_mov_b32 s2, s40
	s_mov_b32 s12, s24
	s_mov_b32 s1, s33
	global_store_dwordx4 v[38:39], v[28:31], off
	s_waitcnt lgkmcnt(3)
	s_nop 0
	v_cvt_pk_bf16_f32 v28, v32, v33
	s_waitcnt lgkmcnt(2)
	v_cvt_pk_bf16_f32 v29, v34, v35
	s_waitcnt lgkmcnt(1)
	v_cvt_pk_bf16_f32 v30, v36, v37
	s_waitcnt lgkmcnt(0)
	v_cvt_pk_bf16_f32 v31, v40, v41
	global_store_dwordx4 v[38:39], v[28:31], off offset:16
	s_barrier
	s_cbranch_vccz .LBB0_258
